# S5 prompt tile: running pointers instead of per-tile address arithmetic
# baseline (speedup 1.0000x reference)
.LBB0_464:
	s_and_b32 s3, s4, 0x7f
	s_lshl_b32 s6, s3, 7
	s_lshl_b32 s28, s3, 6
	v_or_b32_e32 v0, s6, v143
	v_readlane_b32 s18, v254, 20
	v_lshlrev_b32_e32 v0, 2, v0
	v_or_b32_e32 v1, s28, v142
	v_readlane_b32 s19, v254, 21
	s_lshl_b32 s5, s4, 4
	v_lshl_or_b32 v1, v1, 6, v72
	s_nop 2
	global_load_dwordx2 v[80:81], v0, s[18:19]
	global_load_dwordx4 v[32:35], v1, s[76:77]
	global_load_dwordx4 v[36:39], v1, s[76:77] offset:32
	global_load_dwordx4 v[40:43], v1, s[76:77] offset:2048
	v_lshl_or_b32 v0, s3, 12, v105
	s_lshl_b32 s6, s3, 6
	s_and_b32 s5, s5, 0xfffff800
	global_load_dwordx4 v[44:47], v1, s[76:77] offset:2080
	global_load_dwordx4 v[48:51], v0, s[78:79]
	global_load_dwordx4 v[52:55], v0, s[78:79] offset:64
	global_load_dwordx4 v[56:59], v0, s[78:79] offset:128
	global_load_dwordx4 v[60:63], v0, s[78:79] offset:192
	v_lshl_add_u64 v[0:1], v[96:97], 0, s[6:7]
	global_load_dwordx4 v[64:67], v[0:1], off
	v_or_b32_e32 v0, s5, v142
	v_ashrrev_i32_e32 v1, 31, v0
	v_or_b32_e32 v2, s5, v210
	v_lshlrev_b64 v[0:1], 12, v[0:1]
	v_ashrrev_i32_e32 v3, 31, v2
	v_lshl_add_u64 v[0:1], s[20:21], 0, v[0:1]
	s_lshl_b32 s6, s3, 5
	v_lshlrev_b64 v[4:5], 12, v[2:3]
	v_lshl_add_u64 v[0:1], v[0:1], 0, s[6:7]
	v_lshl_add_u64 v[4:5], s[20:21], 0, v[4:5]
	v_lshl_add_u64 v[0:1], v[0:1], 0, v[72:73]
	v_lshl_add_u64 v[4:5], v[4:5], 0, s[6:7]
	v_lshl_add_u64 v[4:5], v[4:5], 0, v[78:79]
	global_load_dwordx4 v[68:71], v[0:1], off
	global_load_dwordx2 v[100:101], v[4:5], off
	v_or_b32_e32 v0, 16, v2
	v_ashrrev_i32_e32 v1, 31, v0
	v_lshlrev_b64 v[0:1], 12, v[0:1]
	v_lshl_add_u64 v[0:1], s[20:21], 0, v[0:1]
	v_lshl_add_u64 v[0:1], v[0:1], 0, s[6:7]
	v_lshl_add_u64 v[0:1], v[0:1], 0, v[78:79]
	global_load_dwordx2 v[94:95], v[0:1], off
	s_and_b32 s3, s17, 0xfffff800
	s_add_u32 s18, s20, s6
	s_addc_u32 s19, s21, 0
	v_or_b32_e32 v109, s3, v144
	v_or_b32_e32 v110, s3, v210
	v_or_b32_e32 v111, s3, v104
	v_lshl_add_u64 v[82:83], v[98:99], 0, s[6:7]
	v_lshl_add_u64 v[84:85], s[18:19], 0, v[72:73]
	v_lshl_add_u64 v[86:87], s[18:19], 0, v[78:79]
	v_lshlrev_b32_e32 v240, 12, v111
	v_mov_b32_e32 v241, 0
	v_lshl_add_u64 v[230:231], v[84:85], 0, v[240:241]
	v_add_u32_e32 v242, 32, v110
	v_lshlrev_b32_e32 v242, 12, v242
	v_mov_b32_e32 v243, 0
	v_lshl_add_u64 v[232:233], v[86:87], 0, v[242:243]
	v_lshlrev_b32_e32 v244, 12, v109
	v_mov_b32_e32 v245, 0
	v_lshl_add_u64 v[234:235], v[86:87], 0, v[244:245]
	v_lshlrev_b32_e32 v246, 12, v110
	v_mov_b32_e32 v247, 0
	v_lshl_add_u64 v[236:237], v[82:83], 0, v[246:247]
	s_mov_b64 s[50:51], 0x10000
	v_lshl_add_u64 v[238:239], v[236:237], 0, s[50:51]
	s_mov_b64 s[50:51], 0x20000
	s_mov_b32 s5, 0
	s_mov_b32 s6, 0
	v_mov_b32_e32 v102, 0
	v_mov_b32_e32 v103, v73
	s_waitcnt vmcnt(12)
	v_xor_b32_e32 v89, 0x80000000, v81
	v_mov_b32_e32 v88, v81
	v_mov_b32_e32 v90, v80
	v_mov_b32_e32 v91, v80
	v_pk_mov_b32 v[92:93], v[88:89], v[88:89] op_sel:[1,0]
	s_waitcnt vmcnt(0)
	s_branch .Ls5p_tile

.Ls5p_ld:
	global_load_dwordx4 v[68:71], v[230:231], off
	global_load_dwordx2 v[190:191], v[232:233], off
	global_load_dwordx2 v[192:193], v[234:235], off
	v_lshl_add_u64 v[230:231], v[230:231], 0, s[50:51]
	v_lshl_add_u64 v[232:233], v[232:233], 0, s[50:51]
	v_lshl_add_u64 v[234:235], v[234:235], 0, s[50:51]
	s_nop 3
.Ls5p_swap:
	v_permlane32_swap_b32_e32 v0, v112
	v_permlane32_swap_b32_e32 v1, v113
	v_permlane32_swap_b32_e32 v2, v114
	v_permlane32_swap_b32_e32 v3, v115
	v_permlane32_swap_b32_e32 v4, v116
	v_permlane32_swap_b32_e32 v5, v117
	v_permlane32_swap_b32_e32 v6, v118
	v_permlane32_swap_b32_e32 v7, v119
	v_permlane32_swap_b32_e32 v8, v120
	v_permlane32_swap_b32_e32 v9, v121
	v_permlane32_swap_b32_e32 v10, v122
	v_permlane32_swap_b32_e32 v11, v123
	v_permlane32_swap_b32_e32 v12, v124
	v_permlane32_swap_b32_e32 v13, v125
	v_permlane32_swap_b32_e32 v14, v126
	v_permlane32_swap_b32_e32 v15, v127
	v_permlane32_swap_b32_e32 v16, v160
	v_permlane32_swap_b32_e32 v17, v161
	v_permlane32_swap_b32_e32 v18, v162
	v_permlane32_swap_b32_e32 v19, v163
	v_permlane32_swap_b32_e32 v20, v164
	v_permlane32_swap_b32_e32 v21, v165
	v_permlane32_swap_b32_e32 v22, v166
	v_permlane32_swap_b32_e32 v23, v167
	v_permlane32_swap_b32_e32 v24, v168
	v_permlane32_swap_b32_e32 v25, v169
	v_permlane32_swap_b32_e32 v26, v170
	v_permlane32_swap_b32_e32 v27, v171
	v_permlane32_swap_b32_e32 v28, v172
	v_permlane32_swap_b32_e32 v29, v173
	v_permlane32_swap_b32_e32 v30, v174
	v_permlane32_swap_b32_e32 v31, v175
	v_fmac_f32_e32 v0, v80, v103
	v_fmac_f32_e32 v16, v80, v102
	v_fmac_f32_e32 v0, v89, v102
	v_fmac_f32_e32 v16, v81, v103
	v_fmac_f32_e32 v1, v80, v0
	v_fmac_f32_e32 v17, v80, v16
	v_cvt_pk_bf16_f32 v134, v0, v16
	v_fmac_f32_e32 v1, v89, v16
	v_fmac_f32_e32 v17, v81, v0
	v_fmac_f32_e32 v2, v80, v1
	v_fmac_f32_e32 v18, v80, v17
	v_cvt_pk_bf16_f32 v135, v1, v17
	v_fmac_f32_e32 v2, v89, v17
	v_fmac_f32_e32 v18, v81, v1
	ds_write_b32 v107, v134
	v_fmac_f32_e32 v3, v80, v2
	v_fmac_f32_e32 v19, v80, v18
	v_cvt_pk_bf16_f32 v136, v2, v18
	v_fmac_f32_e32 v3, v89, v18
	v_fmac_f32_e32 v19, v81, v2
	ds_write_b32 v107, v135 offset:528
	v_fmac_f32_e32 v112, v80, v3
	v_fmac_f32_e32 v160, v80, v19
	v_cvt_pk_bf16_f32 v137, v3, v19
	v_fmac_f32_e32 v112, v89, v19
	v_fmac_f32_e32 v160, v81, v3
	ds_write_b32 v107, v136 offset:1056
	v_fmac_f32_e32 v113, v80, v112
	v_fmac_f32_e32 v161, v80, v160
	v_cvt_pk_bf16_f32 v138, v112, v160
	v_fmac_f32_e32 v113, v89, v160
	v_fmac_f32_e32 v161, v81, v112
	ds_write_b32 v107, v137 offset:1584
	v_fmac_f32_e32 v114, v80, v113
	v_fmac_f32_e32 v162, v80, v161
	v_cvt_pk_bf16_f32 v139, v113, v161
	v_fmac_f32_e32 v114, v89, v161
	v_fmac_f32_e32 v162, v81, v113
	ds_write_b32 v107, v138 offset:2112
	v_fmac_f32_e32 v115, v80, v114
	v_fmac_f32_e32 v163, v80, v162
	v_cvt_pk_bf16_f32 v134, v114, v162
	v_fmac_f32_e32 v115, v89, v162
	v_fmac_f32_e32 v163, v81, v114
	ds_write_b32 v107, v139 offset:2640
	v_fmac_f32_e32 v4, v80, v115
	v_fmac_f32_e32 v20, v80, v163
	v_cvt_pk_bf16_f32 v135, v115, v163
	v_fmac_f32_e32 v4, v89, v163
	v_fmac_f32_e32 v20, v81, v115
	ds_write_b32 v107, v134 offset:3168
	v_fmac_f32_e32 v5, v80, v4
	v_fmac_f32_e32 v21, v80, v20
	v_cvt_pk_bf16_f32 v136, v4, v20
	v_fmac_f32_e32 v5, v89, v20
	v_fmac_f32_e32 v21, v81, v4
	ds_write_b32 v107, v135 offset:3696
	v_fmac_f32_e32 v6, v80, v5
	v_fmac_f32_e32 v22, v80, v21
	v_cvt_pk_bf16_f32 v137, v5, v21
	v_fmac_f32_e32 v6, v89, v21
	v_fmac_f32_e32 v22, v81, v5
	ds_write_b32 v107, v136 offset:4224
	v_fmac_f32_e32 v7, v80, v6
	v_fmac_f32_e32 v23, v80, v22
	v_cvt_pk_bf16_f32 v138, v6, v22
	v_fmac_f32_e32 v7, v89, v22
	v_fmac_f32_e32 v23, v81, v6
	ds_write_b32 v107, v137 offset:4752
	v_fmac_f32_e32 v116, v80, v7
	v_fmac_f32_e32 v164, v80, v23
	v_cvt_pk_bf16_f32 v139, v7, v23
	v_fmac_f32_e32 v116, v89, v23
	v_fmac_f32_e32 v164, v81, v7
	ds_write_b32 v107, v138 offset:5280
	v_fmac_f32_e32 v117, v80, v116
	v_fmac_f32_e32 v165, v80, v164
	v_cvt_pk_bf16_f32 v134, v116, v164
	v_fmac_f32_e32 v117, v89, v164
	v_fmac_f32_e32 v165, v81, v116
	ds_write_b32 v107, v139 offset:5808
	v_fmac_f32_e32 v118, v80, v117
	v_fmac_f32_e32 v166, v80, v165
	v_cvt_pk_bf16_f32 v135, v117, v165
	v_fmac_f32_e32 v118, v89, v165
	v_fmac_f32_e32 v166, v81, v117
	ds_write_b32 v107, v134 offset:6336
	v_fmac_f32_e32 v119, v80, v118
	v_fmac_f32_e32 v167, v80, v166
	v_cvt_pk_bf16_f32 v136, v118, v166
	v_fmac_f32_e32 v119, v89, v166
	v_fmac_f32_e32 v167, v81, v118
	ds_write_b32 v107, v135 offset:6864
	v_fmac_f32_e32 v8, v80, v119
	v_fmac_f32_e32 v24, v80, v167
	v_cvt_pk_bf16_f32 v137, v119, v167
	v_fmac_f32_e32 v8, v89, v167
	v_fmac_f32_e32 v24, v81, v119
	ds_write_b32 v107, v136 offset:7392
	v_fmac_f32_e32 v9, v80, v8
	v_fmac_f32_e32 v25, v80, v24
	v_cvt_pk_bf16_f32 v138, v8, v24
	v_fmac_f32_e32 v9, v89, v24
	v_fmac_f32_e32 v25, v81, v8
	ds_write_b32 v107, v137 offset:7920
	ds_read_b128 v[194:197], v108
	ds_read_b128 v[198:201], v108 offset:64
	ds_read_b128 v[202:205], v108 offset:128
	ds_read_b128 v[206:209], v108 offset:192
	v_fmac_f32_e32 v10, v80, v9
	v_fmac_f32_e32 v26, v80, v25
	v_cvt_pk_bf16_f32 v139, v9, v25
	v_fmac_f32_e32 v10, v89, v25
	v_fmac_f32_e32 v26, v81, v9
	ds_write_b32 v107, v138 offset:8448
	v_fmac_f32_e32 v11, v80, v10
	v_fmac_f32_e32 v27, v80, v26
	v_cvt_pk_bf16_f32 v134, v10, v26
	v_fmac_f32_e32 v11, v89, v26
	v_fmac_f32_e32 v27, v81, v10
	ds_write_b32 v107, v139 offset:8976
	v_fmac_f32_e32 v120, v80, v11
	v_fmac_f32_e32 v168, v80, v27
	v_cvt_pk_bf16_f32 v135, v11, v27
	v_fmac_f32_e32 v120, v89, v27
	v_fmac_f32_e32 v168, v81, v11
	ds_write_b32 v107, v134 offset:9504
	v_fmac_f32_e32 v121, v80, v120
	v_fmac_f32_e32 v169, v80, v168
	v_cvt_pk_bf16_f32 v136, v120, v168
	v_fmac_f32_e32 v121, v89, v168
	v_fmac_f32_e32 v169, v81, v120
	ds_write_b32 v107, v135 offset:10032
	v_fmac_f32_e32 v122, v80, v121
	v_fmac_f32_e32 v170, v80, v169
	v_cvt_pk_bf16_f32 v137, v121, v169
	v_fmac_f32_e32 v122, v89, v169
	v_fmac_f32_e32 v170, v81, v121
	ds_write_b32 v107, v136 offset:10560
	s_waitcnt lgkmcnt(5)
	v_mfma_f32_16x16x32_bf16 v[226:229], v[48:51], v[194:197], 0
	v_fmac_f32_e32 v123, v80, v122
	v_fmac_f32_e32 v171, v80, v170
	v_cvt_pk_bf16_f32 v138, v122, v170
	v_fmac_f32_e32 v123, v89, v170
	v_fmac_f32_e32 v171, v81, v122
	ds_write_b32 v107, v137 offset:11088
	v_mfma_f32_16x16x32_bf16 v[226:229], v[52:55], v[198:201], v[226:229]
	v_fmac_f32_e32 v12, v80, v123
	v_fmac_f32_e32 v28, v80, v171
	v_cvt_pk_bf16_f32 v139, v123, v171
	v_fmac_f32_e32 v12, v89, v171
	v_fmac_f32_e32 v28, v81, v123
	ds_write_b32 v107, v138 offset:11616
	v_mfma_f32_16x16x32_bf16 v[226:229], v[56:59], v[202:205], v[226:229]
	v_fmac_f32_e32 v13, v80, v12
	v_fmac_f32_e32 v29, v80, v28
	v_cvt_pk_bf16_f32 v134, v12, v28
	v_fmac_f32_e32 v13, v89, v28
	v_fmac_f32_e32 v29, v81, v12
	ds_write_b32 v107, v139 offset:12144
	v_mfma_f32_16x16x32_bf16 v[226:229], v[60:63], v[206:209], v[226:229]
	v_fmac_f32_e32 v14, v80, v13
	v_fmac_f32_e32 v30, v80, v29
	v_cvt_pk_bf16_f32 v135, v13, v29
	v_fmac_f32_e32 v14, v89, v29
	v_fmac_f32_e32 v30, v81, v13
	ds_write_b32 v107, v134 offset:12672
	v_fmac_f32_e32 v15, v80, v14
	v_fmac_f32_e32 v31, v80, v30
	v_cvt_pk_bf16_f32 v136, v14, v30
	v_fmac_f32_e32 v15, v89, v30
	v_fmac_f32_e32 v31, v81, v14
	ds_write_b32 v107, v135 offset:13200
	v_fmac_f32_e32 v124, v80, v15
	v_fmac_f32_e32 v172, v80, v31
	v_cvt_pk_bf16_f32 v137, v15, v31
	v_fmac_f32_e32 v124, v89, v31
	v_fmac_f32_e32 v172, v81, v15
	ds_write_b32 v107, v136 offset:13728
	v_fmac_f32_e32 v125, v80, v124
	v_fmac_f32_e32 v173, v80, v172
	v_cvt_pk_bf16_f32 v138, v124, v172
	v_fmac_f32_e32 v125, v89, v172
	v_fmac_f32_e32 v173, v81, v124
	ds_write_b32 v107, v137 offset:14256
	v_fmac_f32_e32 v126, v80, v125
	v_fmac_f32_e32 v174, v80, v173
	v_cvt_pk_bf16_f32 v139, v125, v173
	v_fmac_f32_e32 v126, v89, v173
	v_fmac_f32_e32 v174, v81, v125
	ds_write_b32 v107, v138 offset:14784
	v_fma_f32 v103, v80, v126, v127
	v_fma_f32 v102, v80, v174, v175
	v_cvt_pk_bf16_f32 v134, v126, v174
	v_fmac_f32_e32 v103, v89, v174
	v_fmac_f32_e32 v102, v81, v126
	ds_write_b32 v107, v139 offset:15312
	v_cvt_pk_bf16_f32 v135, v103, v102
	ds_write_b32 v107, v134 offset:15840
	ds_write_b32 v107, v135 offset:16368
	v_mov_b64_e32 v[18:19], s[16:17]
	ds_read_b128 v[194:197], v108 offset:8448
	ds_read_b128 v[198:201], v108 offset:8512
	ds_read_b128 v[202:205], v108 offset:8576
	ds_read_b128 v[206:209], v108 offset:8640
	v_lshlrev_b32_e32 v10, 16, v100
	v_and_b32_e32 v11, 0xffff0000, v100
	v_pk_fma_f32 v[14:15], v[64:65], v[10:11], v[226:227]
	s_nop 0
	v_pk_mul_f32 v[6:7], v[14:15], v[14:15]
	s_nop 0
	v_pk_fma_f32 v[6:7], v[6:7], s[10:11], v[18:19] op_sel_hi:[1,0,0] neg_lo:[1,0,0] neg_hi:[1,0,0]
	s_nop 0
	v_pk_mul_f32 v[6:7], v[14:15], v[6:7]
	s_nop 0
	v_exp_f32_e32 v6, v6
	v_exp_f32_e32 v7, v7
	s_nop 0
	v_pk_add_f32 v[10:11], v[6:7], 1.0 op_sel_hi:[1,0]
	v_lshlrev_b32_e32 v6, 16, v101
	v_and_b32_e32 v7, 0xffff0000, v101
	v_pk_fma_f32 v[20:21], v[66:67], v[6:7], v[228:229]
	v_rcp_f32_e32 v16, v10
	v_pk_mul_f32 v[6:7], v[20:21], v[20:21]
	v_rcp_f32_e32 v17, v11
	v_pk_fma_f32 v[6:7], v[6:7], s[10:11], v[18:19] op_sel_hi:[1,0,0] neg_lo:[1,0,0] neg_hi:[1,0,0]
	s_nop 0
	s_nop 0
	v_pk_mul_f32 v[6:7], v[20:21], v[6:7]
	v_pk_mul_f32 v[24:25], v[14:15], v[16:17]
	v_exp_f32_e32 v12, v6
	v_exp_f32_e32 v13, v7
	s_nop 0
	v_pk_add_f32 v[22:23], v[12:13], 1.0 op_sel_hi:[1,0]
	s_waitcnt lgkmcnt(3)
	v_mfma_f32_16x16x32_bf16 v[6:9], v[48:51], v[194:197], 0
	v_rcp_f32_e32 v22, v22
	v_rcp_f32_e32 v23, v23
	s_waitcnt lgkmcnt(2)
	v_mfma_f32_16x16x32_bf16 v[6:9], v[52:55], v[198:201], v[6:9]
	v_pk_mul_f32 v[20:21], v[20:21], v[22:23]
	v_cvt_pk_bf16_f32 v22, v24, v25
	s_waitcnt lgkmcnt(1)
	v_mfma_f32_16x16x32_bf16 v[6:9], v[56:59], v[202:205], v[6:9]
	s_waitcnt lgkmcnt(0)
	v_mfma_f32_16x16x32_bf16 v[6:9], v[60:63], v[206:209], v[6:9]
	v_lshlrev_b32_e32 v10, 16, v94
	v_and_b32_e32 v11, 0xffff0000, v94
	v_lshlrev_b32_e32 v12, 16, v95
	v_and_b32_e32 v13, 0xffff0000, v95
	s_nop 3
	v_pk_fma_f32 v[6:7], v[64:65], v[10:11], v[6:7]
	v_pk_fma_f32 v[8:9], v[66:67], v[12:13], v[8:9]
	v_pk_mul_f32 v[10:11], v[6:7], v[6:7]
	v_pk_mul_f32 v[12:13], v[8:9], v[8:9]
	v_pk_fma_f32 v[10:11], v[10:11], s[10:11], v[18:19] op_sel_hi:[1,0,0] neg_lo:[1,0,0] neg_hi:[1,0,0]
	v_pk_fma_f32 v[12:13], v[12:13], s[10:11], v[18:19] op_sel_hi:[1,0,0] neg_lo:[1,0,0] neg_hi:[1,0,0]
	v_pk_mul_f32 v[10:11], v[6:7], v[10:11]
	v_pk_mul_f32 v[12:13], v[8:9], v[12:13]
	v_exp_f32_e32 v10, v10
	v_exp_f32_e32 v11, v11
	v_exp_f32_e32 v12, v12
	v_exp_f32_e32 v13, v13
	v_pk_add_f32 v[10:11], v[10:11], 1.0 op_sel_hi:[1,0]
	v_rcp_f32_e32 v10, v10
	v_rcp_f32_e32 v11, v11
	v_pk_add_f32 v[12:13], v[12:13], 1.0 op_sel_hi:[1,0]
	v_cvt_pk_bf16_f32 v23, v20, v21
	global_store_dwordx2 v[236:237], v[22:23], off
	v_rcp_f32_e32 v12, v12
	v_rcp_f32_e32 v13, v13
	v_pk_mul_f32 v[6:7], v[6:7], v[10:11]
	s_nop 0
	s_nop 0
	v_cvt_pk_bf16_f32 v6, v6, v7
	v_pk_mul_f32 v[8:9], v[8:9], v[12:13]
	s_nop 0
	v_cvt_pk_bf16_f32 v7, v8, v9
	global_store_dwordx2 v[238:239], v[6:7], off
	v_lshl_add_u64 v[236:237], v[236:237], 0, s[50:51]
	v_lshl_add_u64 v[238:239], v[238:239], 0, s[50:51]
	s_add_i32 s5, s5, 32
	s_add_i32 s6, s6, 1
	s_waitcnt vmcnt(2)
	v_mov_b64_e32 v[100:101], v[190:191]
	v_mov_b64_e32 v[94:95], v[192:193]
	s_cmp_lt_u32 s6, 64
	s_cbranch_scc1 .Ls5p_tile
	s_branch .LBB0_463
